# speedup vs baseline: 1.0108x; 1.0108x over previous
.Lp8b_eb_ok:
	s_cmp_ge_i32 s0, s9
	s_cbranch_scc1 .LBB0_898
	ds_read_b32 v0, v169
	v_mov_b32_e32 v115, v144
	v_readlane_b32 s34, v208, 46
	v_readlane_b32 s35, v208, 47
	v_readlane_b32 s44, v209, 0
	s_waitcnt lgkmcnt(0)
	v_readfirstlane_b32 s1, v0
	s_cmp_gt_i32 s1, s0
	s_cselect_b32 s1, 0, 32
	s_lshl_b32 s14, s1, 2
	s_or_b32 s14, s14, 0x13040
	v_mov_b32_e32 v0, s14
	ds_read_b32 v0, v0
	s_or_b32 s13, s1, 16
	v_readlane_b32 s48, v209, 4
	v_readlane_b32 s49, v209, 5
	v_mov_b32_e32 v32, v144
	s_waitcnt lgkmcnt(0)
	v_readfirstlane_b32 s14, v0
	s_cmp_gt_i32 s14, s0
	s_cselect_b32 s1, s1, s13
	s_lshl_b32 s14, s1, 2
	s_or_b32 s14, s14, 0x13020
	v_mov_b32_e32 v0, s14
	ds_read_b32 v0, v0
	s_or_b32 s13, s1, 8
	v_readlane_b32 s45, v209, 1
	v_readlane_b32 s46, v209, 2
	v_readlane_b32 s47, v209, 3
	s_waitcnt lgkmcnt(0)
	v_readfirstlane_b32 s14, v0
	s_cmp_gt_i32 s14, s0
	s_cselect_b32 s1, s1, s13
	s_lshl_b32 s14, s1, 2
	s_or_b32 s14, s14, 0x13010
	v_mov_b32_e32 v0, s14
	ds_read_b32 v0, v0
	s_or_b32 s13, s1, 4
	v_readlane_b32 s50, v209, 6
	v_readlane_b32 s51, v209, 7
	s_waitcnt lgkmcnt(0)
	v_readfirstlane_b32 s14, v0
	s_cmp_gt_i32 s14, s0
	s_cselect_b32 s1, s1, s13
	s_lshl_b32 s14, s1, 2
	s_add_i32 s14, s14, 0x13008
	v_mov_b32_e32 v0, s14
	ds_read_b32 v0, v0
	s_add_i32 s13, s1, 2
	s_waitcnt lgkmcnt(0)
	v_readfirstlane_b32 s14, v0
	s_cmp_gt_i32 s14, s0
	s_cselect_b32 s1, s1, s13
	s_lshl_b32 s14, s1, 2
	s_add_i32 s14, s14, 0x13004
	v_mov_b32_e32 v0, s14
	ds_read_b32 v0, v0
	s_add_i32 s13, s1, 1
	s_waitcnt lgkmcnt(0)
	v_readfirstlane_b32 s14, v0
	s_cmp_gt_i32 s14, s0
	s_cselect_b32 s16, s1, s13
	s_lshl_b32 s1, s16, 2
	s_add_i32 s1, s1, 0x13000
	v_mov_b32_e32 v0, s1
	ds_read_b32 v2, v0
	s_lshl_b64 s[14:15], s[16:17], 16
	s_add_u32 s14, s56, s14
	s_addc_u32 s15, s57, s15
	s_waitcnt lgkmcnt(0)
	v_sub_u32_e32 v2, s0, v2
	v_lshlrev_b32_e32 v2, 7, v2
	v_ashrrev_i32_e32 v3, 31, v2
	v_readfirstlane_b32 s13, v115
	v_and_b32_e32 v6, 31, v115
	v_lshlrev_b64 v[4:5], 2, v[2:3]
	ds_read_b32 v7, v0 offset:260
	v_lshl_add_u64 v[4:5], s[14:15], 0, v[4:5]
	v_and_or_b32 v0, s13, 64, v6
	v_lshlrev_b32_e32 v6, 2, v0
	v_readfirstlane_b32 s14, v4
	v_readfirstlane_b32 s15, v5
	v_or_b32_e32 v4, v0, v2
	s_waitcnt lgkmcnt(0)
	v_cmp_lt_i32_e32 vcc, v4, v7
	s_ashr_i32 s1, s0, 31
	s_lshl_b64 s[0:1], s[0:1], 16
	global_load_dword v3, v6, s[14:15]
	s_waitcnt vmcnt(0)
	v_cndmask_b32_e32 v120, -1, v3, vcc
	v_max_i32_e32 v0, 0, v120
	v_lshl_add_u64 v[2:3], v[0:1], 2, s[34:35]
	global_load_dword v116, v[2:3], off
	global_load_dword v0, v6, s[14:15] offset:128
	v_or_b32_e32 v2, 32, v4
	v_cmp_lt_i32_e32 vcc, v2, v7
	s_add_i32 s14, s16, s8
	s_ashr_i32 s15, s14, 31
	s_waitcnt vmcnt(0)
	v_cndmask_b32_e32 v118, -1, v0, vcc
	v_max_i32_e32 v0, 0, v118
	v_lshl_add_u64 v[2:3], v[0:1], 2, s[34:35]
	global_load_dword v114, v[2:3], off
	s_lshl_b64 s[34:35], s[14:15], 20
	s_and_b32 s14, s11, 0x380
	v_ashrrev_i32_e32 v2, 3, v115
	s_add_u32 s0, s78, s0
	v_ashrrev_i32_e32 v3, 31, v2
	s_addc_u32 s1, s79, s1
	v_lshlrev_b64 v[2:3], 9, v[2:3]
	v_lshl_add_u64 v[2:3], s[0:1], 0, v[2:3]
	s_add_u32 s0, s48, s34
	s_addc_u32 s1, s49, s35
	s_lshl_b32 s15, s14, 2
	s_add_u32 s0, s0, s15
	v_lshlrev_b32_e32 v0, 4, v115
	s_addc_u32 s1, s1, 0
	v_ashrrev_i32_e32 v30, 5, v32
	v_and_b32_e32 v0, 0x1f0, v0
	v_ashrrev_i32_e32 v31, 31, v30
	v_lshl_add_u64 v[4:5], s[0:1], 0, v[0:1]
	v_lshlrev_b64 v[6:7], 12, v[30:31]
	v_lshl_add_u64 v[124:125], v[4:5], 0, v[6:7]
	v_add_co_u32_e32 v126, vcc, s72, v124
	global_load_dwordx4 v[18:21], v[124:125], off
	s_nop 0
	v_addc_co_u32_e32 v127, vcc, 0, v125, vcc
	v_add_co_u32_e32 v128, vcc, s33, v124
	s_mov_b32 s1, 0x28000
	s_nop 0
	v_addc_co_u32_e32 v129, vcc, 0, v125, vcc
	v_add_co_u32_e32 v130, vcc, s36, v124
	v_lshlrev_b32_e32 v0, 4, v32
	s_nop 0
	v_addc_co_u32_e32 v131, vcc, 0, v125, vcc
	v_add_co_u32_e32 v132, vcc, s87, v124
	v_and_b32_e32 v0, 0x70, v0
	s_nop 0
	v_addc_co_u32_e32 v133, vcc, 0, v125, vcc
	v_add_co_u32_e32 v134, vcc, s1, v124
	s_mov_b32 s1, 0x30000
	s_nop 0
	v_addc_co_u32_e32 v135, vcc, 0, v125, vcc
	v_lshl_add_u64 v[122:123], v[2:3], 0, v[0:1]
	global_load_dwordx4 v[2:5], v[126:127], off
	v_add_co_u32_e32 v136, vcc, s1, v124
	global_load_dwordx4 v[6:9], v[128:129], off
	global_load_dwordx4 v[10:13], v[130:131], off
	v_addc_co_u32_e32 v137, vcc, 0, v125, vcc
	s_mov_b32 s1, 0x38000
	global_load_dwordx4 v[14:17], v[132:133], off
	global_load_dwordx4 v[22:25], v[134:135], off
	v_add_co_u32_e32 v138, vcc, s1, v124
	global_load_dwordx4 v[26:29], v[136:137], off
	s_nop 0
	v_addc_co_u32_e32 v139, vcc, 0, v125, vcc
	global_load_dwordx4 v[34:37], v[138:139], off
	global_load_dwordx4 v[38:41], v[122:123], off
	s_movk_i32 s1, 0x4000
	v_add_co_u32_e32 v154, vcc, s1, v122
	s_mov_b32 s1, 0xc000
	s_nop 0
	v_addc_co_u32_e32 v155, vcc, 0, v123, vcc
	v_add_co_u32_e32 v156, vcc, s72, v122
	global_load_dwordx4 v[42:45], v[154:155], off
	s_nop 0
	v_addc_co_u32_e32 v157, vcc, 0, v123, vcc
	v_add_co_u32_e32 v158, vcc, s1, v122
	global_load_dwordx4 v[46:49], v[156:157], off
	s_nop 0
	v_addc_co_u32_e32 v159, vcc, 0, v123, vcc
	global_load_dwordx4 v[50:53], v[158:159], off
	v_lshlrev_b32_e32 v33, 2, v32
	s_movk_i32 s1, 0x7c
	s_mov_b64 s[34:35], 0x4000
	v_lshl_add_u64 v[142:143], v[122:123], 0, s[34:35]
	s_mov_b64 s[34:35], 0x8000
	v_lshrrev_b32_e32 v31, 3, v32
	v_lshl_add_u64 v[150:151], v[122:123], 0, s[34:35]
	s_mov_b64 s[34:35], 0xc000
	v_readfirstlane_b32 s0, v32
	v_lshl_add_u64 v[152:153], v[122:123], 0, s[34:35]
	v_lshlrev_b32_e32 v54, 3, v32
	s_waitcnt vmcnt(11)
	v_cvt_pk_bf16_f32 v18, v18, v19
	v_cvt_pk_bf16_f32 v19, v20, v21
	v_and_b32_e32 v20, 0x60, v32
	v_bitop3_b32 v20, v33, v20, s1 bitop3:0x6c
	v_lshlrev_b32_e32 v20, 1, v20
	v_lshl_or_b32 v117, v30, 8, v20
	s_movk_i32 s1, 0x90
	v_mad_u64_u32 v[140:141], s[34:35], v31, s1, v[0:1]
	v_and_b32_e32 v0, 31, v32
	v_and_or_b32 v0, s0, 64, v0
	s_ashr_i32 s0, s0, 1
	s_andn2_b32 s0, s0, 63
	s_waitcnt vmcnt(10)
	v_cvt_pk_bf16_f32 v2, v2, v3
	v_cvt_pk_bf16_f32 v3, v4, v5
	ds_write2st64_b64 v117, v[18:19], v[2:3] offset1:4
	s_waitcnt vmcnt(9)
	v_cvt_pk_bf16_f32 v2, v6, v7
	v_cvt_pk_bf16_f32 v3, v8, v9
	s_waitcnt vmcnt(8)
	v_cvt_pk_bf16_f32 v4, v10, v11
	v_cvt_pk_bf16_f32 v5, v12, v13
	ds_write2st64_b64 v117, v[2:3], v[4:5] offset0:8 offset1:12
	s_waitcnt vmcnt(7)
	v_cvt_pk_bf16_f32 v2, v14, v15
	v_cvt_pk_bf16_f32 v3, v16, v17
	s_waitcnt vmcnt(6)
	v_cvt_pk_bf16_f32 v4, v22, v23
	v_cvt_pk_bf16_f32 v5, v24, v25
	ds_write2st64_b64 v117, v[2:3], v[4:5] offset0:16 offset1:20
	s_waitcnt vmcnt(5)
	v_cvt_pk_bf16_f32 v2, v26, v27
	v_cvt_pk_bf16_f32 v3, v28, v29
	s_waitcnt vmcnt(4)
	v_cvt_pk_bf16_f32 v4, v34, v35
	v_cvt_pk_bf16_f32 v5, v36, v37
	ds_write2st64_b64 v117, v[2:3], v[4:5] offset0:24 offset1:28
	v_lshrrev_b32_e32 v2, 1, v32
	v_and_b32_e32 v2, 16, v2
	v_mad_u32_u24 v0, v0, s1, v2
	v_and_b32_e32 v2, 16, v32
	v_and_or_b32 v2, v33, 12, v2
	v_and_b32_e32 v4, 0x60, v54
	v_or_b32_e32 v3, s0, v2
	v_bitop3_b32 v5, v2, v4, s0 bitop3:0x36
	s_mov_b32 s0, 0x40000
	v_add_co_u32_e32 v2, vcc, s0, v124
	v_bitop3_b32 v14, v3, v4, 32 bitop3:0x36
	s_nop 0
	v_addc_co_u32_e32 v3, vcc, 0, v125, vcc
	s_mov_b32 s0, 0x48000
	s_waitcnt vmcnt(3)
	ds_write_b128 v140, v[38:41] offset:32768
	s_waitcnt vmcnt(2)
	ds_write_b128 v140, v[42:45] offset:37376
	s_waitcnt vmcnt(1)
	ds_write_b128 v140, v[46:49] offset:41984
	s_waitcnt vmcnt(0)
	ds_write_b128 v140, v[50:53] offset:46592
	s_waitcnt lgkmcnt(0)
	s_barrier
	global_load_dwordx4 v[66:69], v[2:3], off
	v_add_co_u32_e32 v2, vcc, s0, v124
	s_mov_b32 s0, 0x50000
	s_nop 0
	v_addc_co_u32_e32 v3, vcc, 0, v125, vcc
	global_load_dwordx4 v[70:73], v[2:3], off
	v_add_co_u32_e32 v2, vcc, s0, v124
	s_mov_b32 s0, 0x58000
	s_nop 0
	v_addc_co_u32_e32 v3, vcc, 0, v125, vcc
	global_load_dwordx4 v[74:77], v[2:3], off
	v_add_co_u32_e32 v2, vcc, s0, v124
	s_mov_b32 s0, 0x60000
	s_nop 0
	v_addc_co_u32_e32 v3, vcc, 0, v125, vcc
	global_load_dwordx4 v[78:81], v[2:3], off
	v_add_co_u32_e32 v2, vcc, s0, v124
	s_mov_b32 s0, 0x68000
	s_nop 0
	v_addc_co_u32_e32 v3, vcc, 0, v125, vcc
	global_load_dwordx4 v[82:85], v[2:3], off
	v_add_co_u32_e32 v2, vcc, s0, v124
	s_mov_b32 s0, 0x70000
	s_nop 0
	v_addc_co_u32_e32 v3, vcc, 0, v125, vcc
	global_load_dwordx4 v[86:89], v[2:3], off
	v_add_co_u32_e32 v2, vcc, s0, v124
	s_mov_b32 s0, 0x78000
	s_nop 0
	v_addc_co_u32_e32 v3, vcc, 0, v125, vcc
	global_load_dwordx4 v[90:93], v[2:3], off
	v_add_co_u32_e32 v2, vcc, s0, v124
	s_nop 1
	v_addc_co_u32_e32 v3, vcc, 0, v125, vcc
	global_load_dwordx4 v[110:113], v[2:3], off
	global_load_dwordx4 v[94:97], v[122:123], off offset:128
	global_load_dwordx4 v[98:101], v[142:143], off offset:128
	global_load_dwordx4 v[102:105], v[150:151], off offset:128
	global_load_dwordx4 v[106:109], v[152:153], off offset:128
	v_lshlrev_b32_e32 v2, 6, v32
	v_and_b32_e32 v15, 0xb00, v2
	v_lshl_add_u32 v121, v5, 1, v15
	v_lshl_add_u32 v119, v14, 1, v15
	ds_read_b64_tr_b16 v[2:3], v121
	ds_read_b64_tr_b16 v[4:5], v121 offset:1024
	ds_read_b128 v[6:9], v0 offset:32768
	ds_read_b128 v[10:13], v0 offset:37376
	ds_read_b64_tr_b16 v[14:15], v119
	ds_read_b64_tr_b16 v[16:17], v119 offset:1024
	ds_read_b64_tr_b16 v[186:187], v121 offset:4096
	ds_read_b64_tr_b16 v[188:189], v121 offset:5120
	ds_read_b128 v[190:193], v0 offset:32800
	ds_read_b128 v[194:197], v0 offset:37408
	ds_read_b64_tr_b16 v[198:199], v119 offset:4096
	ds_read_b64_tr_b16 v[200:201], v119 offset:5120
	s_waitcnt lgkmcnt(9)
	v_mfma_f32_32x32x16_bf16 v[50:65], v[2:5], v[6:9], 0
	s_waitcnt lgkmcnt(8)
	v_mfma_f32_32x32x16_bf16 v[18:33], v[2:5], v[10:13], 0
	s_waitcnt lgkmcnt(6)
	v_mfma_f32_32x32x16_bf16 v[34:49], v[14:17], v[6:9], 0
	v_mfma_f32_32x32x16_bf16 v[2:17], v[14:17], v[10:13], 0
	s_waitcnt lgkmcnt(3)
	v_mfma_f32_32x32x16_bf16 v[50:65], v[186:189], v[190:193], v[50:65]
	s_waitcnt lgkmcnt(2)
	v_mfma_f32_32x32x16_bf16 v[18:33], v[186:189], v[194:197], v[18:33]
	s_waitcnt lgkmcnt(0)
	v_mfma_f32_32x32x16_bf16 v[34:49], v[198:201], v[190:193], v[34:49]
	ds_read_b64_tr_b16 v[186:187], v121 offset:8192
	ds_read_b64_tr_b16 v[188:189], v121 offset:9216
	ds_read_b128 v[190:193], v0 offset:32832
	v_mfma_f32_32x32x16_bf16 v[2:17], v[198:201], v[194:197], v[2:17]
	ds_read_b128 v[194:197], v0 offset:37440
	ds_read_b64_tr_b16 v[198:199], v119 offset:8192
	ds_read_b64_tr_b16 v[200:201], v119 offset:9216
	s_waitcnt lgkmcnt(3)
	v_mfma_f32_32x32x16_bf16 v[50:65], v[186:189], v[190:193], v[50:65]
	s_waitcnt lgkmcnt(2)
	v_mfma_f32_32x32x16_bf16 v[18:33], v[186:189], v[194:197], v[18:33]
	s_waitcnt lgkmcnt(0)
	v_mfma_f32_32x32x16_bf16 v[34:49], v[198:201], v[190:193], v[34:49]
	ds_read_b64_tr_b16 v[186:187], v121 offset:12288
	ds_read_b64_tr_b16 v[188:189], v121 offset:13312
	ds_read_b128 v[190:193], v0 offset:32864
	v_mfma_f32_32x32x16_bf16 v[2:17], v[198:201], v[194:197], v[2:17]
	ds_read_b128 v[194:197], v0 offset:37472
	ds_read_b64_tr_b16 v[198:199], v119 offset:12288
	ds_read_b64_tr_b16 v[200:201], v119 offset:13312
	s_waitcnt lgkmcnt(3)
	v_mfma_f32_32x32x16_bf16 v[50:65], v[186:189], v[190:193], v[50:65]
	s_waitcnt lgkmcnt(2)
	v_mfma_f32_32x32x16_bf16 v[18:33], v[186:189], v[194:197], v[18:33]
	s_waitcnt lgkmcnt(0)
	v_mfma_f32_32x32x16_bf16 v[34:49], v[198:201], v[190:193], v[34:49]
	v_mfma_f32_32x32x16_bf16 v[2:17], v[198:201], v[194:197], v[2:17]
	s_waitcnt vmcnt(11)
	v_cvt_pk_bf16_f32 v66, v66, v67
	v_cvt_pk_bf16_f32 v67, v68, v69
	s_waitcnt vmcnt(10)
	v_cvt_pk_bf16_f32 v68, v70, v71
	v_cvt_pk_bf16_f32 v69, v72, v73
	ds_write2st64_b64 v117, v[66:67], v[68:69] offset0:32 offset1:36
	s_waitcnt vmcnt(9)
	v_cvt_pk_bf16_f32 v66, v74, v75
	v_cvt_pk_bf16_f32 v67, v76, v77
	s_waitcnt vmcnt(8)
	v_cvt_pk_bf16_f32 v68, v78, v79
	v_cvt_pk_bf16_f32 v69, v80, v81
	ds_write2st64_b64 v117, v[66:67], v[68:69] offset0:40 offset1:44
	s_waitcnt vmcnt(7)
	v_cvt_pk_bf16_f32 v66, v82, v83
	v_cvt_pk_bf16_f32 v67, v84, v85
	s_waitcnt vmcnt(6)
	v_cvt_pk_bf16_f32 v68, v86, v87
	v_cvt_pk_bf16_f32 v69, v88, v89
	ds_write2st64_b64 v117, v[66:67], v[68:69] offset0:48 offset1:52
	s_waitcnt vmcnt(5)
	v_cvt_pk_bf16_f32 v66, v90, v91
	v_cvt_pk_bf16_f32 v67, v92, v93
	s_waitcnt vmcnt(4)
	v_cvt_pk_bf16_f32 v68, v110, v111
	v_cvt_pk_bf16_f32 v69, v112, v113
	s_mov_b32 s0, 0x80000
	ds_write2st64_b64 v117, v[66:67], v[68:69] offset0:56 offset1:60
	s_waitcnt vmcnt(3)
	ds_write_b128 v140, v[94:97] offset:51200
	s_waitcnt vmcnt(2)
	ds_write_b128 v140, v[98:101] offset:55808
	s_waitcnt vmcnt(1)
	ds_write_b128 v140, v[102:105] offset:60416
	s_waitcnt vmcnt(0)
	ds_write_b128 v140, v[106:109] offset:65024
	v_add_co_u32_e32 v66, vcc, s0, v124
	s_mov_b32 s0, 0x88000
	s_nop 0
	v_addc_co_u32_e32 v67, vcc, 0, v125, vcc
	v_add_co_u32_e32 v70, vcc, s0, v124
	s_mov_b32 s0, 0x90000
	s_nop 0
	v_addc_co_u32_e32 v71, vcc, 0, v125, vcc
	v_add_co_u32_e32 v74, vcc, s0, v124
	s_mov_b32 s0, 0x98000
	s_nop 0
	v_addc_co_u32_e32 v75, vcc, 0, v125, vcc
	v_add_co_u32_e32 v78, vcc, s0, v124
	s_mov_b32 s0, 0xa0000
	s_nop 0
	v_addc_co_u32_e32 v79, vcc, 0, v125, vcc
	v_add_co_u32_e32 v82, vcc, s0, v124
	s_mov_b32 s0, 0xa8000
	s_nop 0
	v_addc_co_u32_e32 v83, vcc, 0, v125, vcc
	v_add_co_u32_e32 v86, vcc, s0, v124
	s_mov_b32 s0, 0xb0000
	s_nop 0
	v_addc_co_u32_e32 v87, vcc, 0, v125, vcc
	v_add_co_u32_e32 v90, vcc, s0, v124
	s_mov_b32 s0, 0xb8000
	s_nop 0
	v_addc_co_u32_e32 v91, vcc, 0, v125, vcc
	v_add_co_u32_e32 v94, vcc, s0, v124
	s_waitcnt lgkmcnt(0)
	s_nop 0
	v_addc_co_u32_e32 v95, vcc, 0, v125, vcc
	s_barrier
	global_load_dwordx4 v[66:69], v[66:67], off
	s_nop 0
	global_load_dwordx4 v[70:73], v[70:71], off
	s_nop 0
	global_load_dwordx4 v[74:77], v[74:75], off
	s_nop 0
	global_load_dwordx4 v[78:81], v[78:79], off
	s_nop 0
	global_load_dwordx4 v[82:85], v[82:83], off
	s_nop 0
	global_load_dwordx4 v[86:89], v[86:87], off
	s_nop 0
	global_load_dwordx4 v[90:93], v[90:91], off
	s_nop 0
	global_load_dwordx4 v[94:97], v[94:95], off
	s_nop 0
	global_load_dwordx4 v[98:101], v[122:123], off offset:256
	global_load_dwordx4 v[102:105], v[142:143], off offset:256
	global_load_dwordx4 v[106:109], v[150:151], off offset:256
	global_load_dwordx4 v[110:113], v[152:153], off offset:256
	ds_read_b64_tr_b16 v[186:187], v121 offset:16384
	ds_read_b64_tr_b16 v[188:189], v121 offset:17408
	ds_read_b128 v[190:193], v0 offset:51200
	ds_read_b128 v[194:197], v0 offset:55808
	ds_read_b64_tr_b16 v[198:199], v119 offset:16384
	ds_read_b64_tr_b16 v[200:201], v119 offset:17408
	s_waitcnt lgkmcnt(2)
	v_mfma_f32_32x32x16_bf16 v[18:33], v[186:189], v[194:197], v[18:33]
	v_mfma_f32_32x32x16_bf16 v[50:65], v[186:189], v[190:193], v[50:65]
	s_waitcnt lgkmcnt(0)
	v_mfma_f32_32x32x16_bf16 v[34:49], v[198:201], v[190:193], v[34:49]
	ds_read_b64_tr_b16 v[186:187], v121 offset:20480
	ds_read_b64_tr_b16 v[188:189], v121 offset:21504
	ds_read_b128 v[190:193], v0 offset:51232
	v_mfma_f32_32x32x16_bf16 v[2:17], v[198:201], v[194:197], v[2:17]
	ds_read_b128 v[194:197], v0 offset:55840
	ds_read_b64_tr_b16 v[198:199], v119 offset:20480
	ds_read_b64_tr_b16 v[200:201], v119 offset:21504
	s_waitcnt lgkmcnt(3)
	v_mfma_f32_32x32x16_bf16 v[50:65], v[186:189], v[190:193], v[50:65]
	s_waitcnt lgkmcnt(2)
	v_mfma_f32_32x32x16_bf16 v[18:33], v[186:189], v[194:197], v[18:33]
	s_waitcnt lgkmcnt(0)
	v_mfma_f32_32x32x16_bf16 v[34:49], v[198:201], v[190:193], v[34:49]
	ds_read_b64_tr_b16 v[186:187], v121 offset:24576
	ds_read_b64_tr_b16 v[188:189], v121 offset:25600
	ds_read_b128 v[190:193], v0 offset:51264
	v_mfma_f32_32x32x16_bf16 v[2:17], v[198:201], v[194:197], v[2:17]
	ds_read_b128 v[194:197], v0 offset:55872
	ds_read_b64_tr_b16 v[198:199], v119 offset:24576
	ds_read_b64_tr_b16 v[200:201], v119 offset:25600
	s_waitcnt lgkmcnt(3)
	v_mfma_f32_32x32x16_bf16 v[50:65], v[186:189], v[190:193], v[50:65]
	s_waitcnt lgkmcnt(2)
	v_mfma_f32_32x32x16_bf16 v[18:33], v[186:189], v[194:197], v[18:33]
	s_waitcnt lgkmcnt(0)
	v_mfma_f32_32x32x16_bf16 v[34:49], v[198:201], v[190:193], v[34:49]
	ds_read_b64_tr_b16 v[186:187], v121 offset:28672
	ds_read_b64_tr_b16 v[188:189], v121 offset:29696
	ds_read_b128 v[190:193], v0 offset:51296
	v_mfma_f32_32x32x16_bf16 v[2:17], v[198:201], v[194:197], v[2:17]
	ds_read_b128 v[194:197], v0 offset:55904
	ds_read_b64_tr_b16 v[198:199], v119 offset:28672
	ds_read_b64_tr_b16 v[200:201], v119 offset:29696
	s_waitcnt lgkmcnt(3)
	v_mfma_f32_32x32x16_bf16 v[50:65], v[186:189], v[190:193], v[50:65]
	s_waitcnt lgkmcnt(2)
	v_mfma_f32_32x32x16_bf16 v[18:33], v[186:189], v[194:197], v[18:33]
	s_waitcnt lgkmcnt(0)
	v_mfma_f32_32x32x16_bf16 v[34:49], v[198:201], v[190:193], v[34:49]
	v_mfma_f32_32x32x16_bf16 v[2:17], v[198:201], v[194:197], v[2:17]
	s_waitcnt vmcnt(11)
	v_cvt_pk_bf16_f32 v66, v66, v67
	v_cvt_pk_bf16_f32 v67, v68, v69
	s_waitcnt vmcnt(10)
	v_cvt_pk_bf16_f32 v68, v70, v71
	v_cvt_pk_bf16_f32 v69, v72, v73
	ds_write2st64_b64 v117, v[66:67], v[68:69] offset1:4
	s_waitcnt vmcnt(9)
	v_cvt_pk_bf16_f32 v66, v74, v75
	v_cvt_pk_bf16_f32 v67, v76, v77
	s_waitcnt vmcnt(8)
	v_cvt_pk_bf16_f32 v68, v78, v79
	v_cvt_pk_bf16_f32 v69, v80, v81
	ds_write2st64_b64 v117, v[66:67], v[68:69] offset0:8 offset1:12
	s_waitcnt vmcnt(7)
	v_cvt_pk_bf16_f32 v66, v82, v83
	v_cvt_pk_bf16_f32 v67, v84, v85
	s_waitcnt vmcnt(6)
	v_cvt_pk_bf16_f32 v68, v86, v87
	v_cvt_pk_bf16_f32 v69, v88, v89
	ds_write2st64_b64 v117, v[66:67], v[68:69] offset0:16 offset1:20
	s_waitcnt vmcnt(5)
	v_cvt_pk_bf16_f32 v66, v90, v91
	v_cvt_pk_bf16_f32 v67, v92, v93
	s_waitcnt vmcnt(4)
	v_cvt_pk_bf16_f32 v68, v94, v95
	v_cvt_pk_bf16_f32 v69, v96, v97
	s_mov_b32 s0, 0xc0000
	ds_write2st64_b64 v117, v[66:67], v[68:69] offset0:24 offset1:28
	s_waitcnt vmcnt(3)
	ds_write_b128 v140, v[98:101] offset:32768
	s_waitcnt vmcnt(2)
	ds_write_b128 v140, v[102:105] offset:37376
	s_waitcnt vmcnt(1)
	ds_write_b128 v140, v[106:109] offset:41984
	s_waitcnt vmcnt(0)
	ds_write_b128 v140, v[110:113] offset:46592
	v_add_co_u32_e32 v66, vcc, s0, v124
	s_mov_b32 s0, 0xc8000
	s_nop 0
	v_addc_co_u32_e32 v67, vcc, 0, v125, vcc
	v_add_co_u32_e32 v70, vcc, s0, v124
	s_mov_b32 s0, 0xd0000
	s_nop 0
	v_addc_co_u32_e32 v71, vcc, 0, v125, vcc
	v_add_co_u32_e32 v74, vcc, s0, v124
	s_mov_b32 s0, 0xd8000
	s_nop 0
	v_addc_co_u32_e32 v75, vcc, 0, v125, vcc
	v_add_co_u32_e32 v78, vcc, s0, v124
	s_mov_b32 s0, 0xe0000
	s_nop 0
	v_addc_co_u32_e32 v79, vcc, 0, v125, vcc
	v_add_co_u32_e32 v82, vcc, s0, v124
	s_mov_b32 s0, 0xe8000
	s_nop 0
	v_addc_co_u32_e32 v83, vcc, 0, v125, vcc
	v_add_co_u32_e32 v86, vcc, s0, v124
	s_mov_b32 s0, 0xf0000
	s_nop 0
	v_addc_co_u32_e32 v87, vcc, 0, v125, vcc
	v_add_co_u32_e32 v90, vcc, s0, v124
	s_mov_b32 s0, 0xf8000
	s_nop 0
	v_addc_co_u32_e32 v91, vcc, 0, v125, vcc
	v_add_co_u32_e32 v94, vcc, s0, v124
	s_waitcnt lgkmcnt(0)
	s_nop 0
	v_addc_co_u32_e32 v95, vcc, 0, v125, vcc
	s_barrier
	global_load_dwordx4 v[66:69], v[66:67], off
	s_nop 0
	global_load_dwordx4 v[70:73], v[70:71], off
	s_nop 0
	global_load_dwordx4 v[74:77], v[74:75], off
	s_nop 0
	global_load_dwordx4 v[78:81], v[78:79], off
	s_nop 0
	global_load_dwordx4 v[82:85], v[82:83], off
	s_nop 0
	global_load_dwordx4 v[86:89], v[86:87], off
	s_nop 0
	global_load_dwordx4 v[90:93], v[90:91], off
	s_nop 0
	global_load_dwordx4 v[94:97], v[94:95], off
	s_nop 0
	global_load_dwordx4 v[98:101], v[122:123], off offset:384
	global_load_dwordx4 v[102:105], v[142:143], off offset:384
	global_load_dwordx4 v[106:109], v[150:151], off offset:384
	global_load_dwordx4 v[110:113], v[152:153], off offset:384
	ds_read_b64_tr_b16 v[150:151], v121
	ds_read_b64_tr_b16 v[152:153], v121 offset:1024
	ds_read_b128 v[186:189], v0 offset:32768
	ds_read_b128 v[190:193], v0 offset:37376
	ds_read_b64_tr_b16 v[194:195], v119
	ds_read_b64_tr_b16 v[196:197], v119 offset:1024
	s_waitcnt lgkmcnt(2)
	v_mfma_f32_32x32x16_bf16 v[18:33], v[150:153], v[190:193], v[18:33]
	v_mfma_f32_32x32x16_bf16 v[50:65], v[150:153], v[186:189], v[50:65]
	s_waitcnt lgkmcnt(0)
	v_mfma_f32_32x32x16_bf16 v[34:49], v[194:197], v[186:189], v[34:49]
	ds_read_b64_tr_b16 v[150:151], v121 offset:4096
	ds_read_b64_tr_b16 v[152:153], v121 offset:5120
	ds_read_b128 v[186:189], v0 offset:32800
	v_mfma_f32_32x32x16_bf16 v[2:17], v[194:197], v[190:193], v[2:17]
	ds_read_b128 v[190:193], v0 offset:37408
	ds_read_b64_tr_b16 v[194:195], v119 offset:4096
	ds_read_b64_tr_b16 v[196:197], v119 offset:5120
	s_waitcnt lgkmcnt(3)
	v_mfma_f32_32x32x16_bf16 v[50:65], v[150:153], v[186:189], v[50:65]
	s_waitcnt lgkmcnt(2)
	v_mfma_f32_32x32x16_bf16 v[18:33], v[150:153], v[190:193], v[18:33]
	s_waitcnt lgkmcnt(0)
	v_mfma_f32_32x32x16_bf16 v[34:49], v[194:197], v[186:189], v[34:49]
	ds_read_b64_tr_b16 v[150:151], v121 offset:8192
	ds_read_b64_tr_b16 v[152:153], v121 offset:9216
	ds_read_b128 v[186:189], v0 offset:32832
	v_mfma_f32_32x32x16_bf16 v[2:17], v[194:197], v[190:193], v[2:17]
	ds_read_b128 v[190:193], v0 offset:37440
	ds_read_b64_tr_b16 v[194:195], v119 offset:8192
	ds_read_b64_tr_b16 v[196:197], v119 offset:9216
	s_waitcnt lgkmcnt(3)
	v_mfma_f32_32x32x16_bf16 v[50:65], v[150:153], v[186:189], v[50:65]
	s_waitcnt lgkmcnt(2)
	v_mfma_f32_32x32x16_bf16 v[18:33], v[150:153], v[190:193], v[18:33]
	s_waitcnt lgkmcnt(0)
	v_mfma_f32_32x32x16_bf16 v[34:49], v[194:197], v[186:189], v[34:49]
	ds_read_b64_tr_b16 v[150:151], v121 offset:12288
	ds_read_b64_tr_b16 v[152:153], v121 offset:13312
	ds_read_b128 v[186:189], v0 offset:32864
	v_mfma_f32_32x32x16_bf16 v[2:17], v[194:197], v[190:193], v[2:17]
	ds_read_b128 v[190:193], v0 offset:37472
	ds_read_b64_tr_b16 v[194:195], v119 offset:12288
	ds_read_b64_tr_b16 v[196:197], v119 offset:13312
	s_waitcnt lgkmcnt(3)
	v_mfma_f32_32x32x16_bf16 v[50:65], v[150:153], v[186:189], v[50:65]
	s_waitcnt lgkmcnt(2)
	v_mfma_f32_32x32x16_bf16 v[18:33], v[150:153], v[190:193], v[18:33]
	s_waitcnt lgkmcnt(0)
	v_mfma_f32_32x32x16_bf16 v[34:49], v[194:197], v[186:189], v[34:49]
	v_mfma_f32_32x32x16_bf16 v[2:17], v[194:197], v[190:193], v[2:17]
	s_waitcnt vmcnt(11)
	v_cvt_pk_bf16_f32 v66, v66, v67
	v_cvt_pk_bf16_f32 v67, v68, v69
	s_waitcnt vmcnt(10)
	v_cvt_pk_bf16_f32 v68, v70, v71
	v_cvt_pk_bf16_f32 v69, v72, v73
	ds_write2st64_b64 v117, v[66:67], v[68:69] offset0:32 offset1:36
	s_waitcnt vmcnt(9)
	v_cvt_pk_bf16_f32 v66, v74, v75
	v_cvt_pk_bf16_f32 v67, v76, v77
	s_waitcnt vmcnt(8)
	v_cvt_pk_bf16_f32 v68, v78, v79
	v_cvt_pk_bf16_f32 v69, v80, v81
	ds_write2st64_b64 v117, v[66:67], v[68:69] offset0:40 offset1:44
	s_waitcnt vmcnt(7)
	v_cvt_pk_bf16_f32 v66, v82, v83
	v_cvt_pk_bf16_f32 v67, v84, v85
	s_waitcnt vmcnt(6)
	v_cvt_pk_bf16_f32 v68, v86, v87
	v_cvt_pk_bf16_f32 v69, v88, v89
	ds_write2st64_b64 v117, v[66:67], v[68:69] offset0:48 offset1:52
	s_waitcnt vmcnt(5)
	v_cvt_pk_bf16_f32 v66, v90, v91
	v_cvt_pk_bf16_f32 v67, v92, v93
	s_waitcnt vmcnt(4)
	v_cvt_pk_bf16_f32 v68, v94, v95
	v_cvt_pk_bf16_f32 v69, v96, v97
	ds_write2st64_b64 v117, v[66:67], v[68:69] offset0:56 offset1:60
	s_waitcnt vmcnt(3)
	ds_write_b128 v140, v[98:101] offset:51200
	s_waitcnt vmcnt(2)
	ds_write_b128 v140, v[102:105] offset:55808
	s_waitcnt vmcnt(1)
	ds_write_b128 v140, v[106:109] offset:60416
	s_waitcnt vmcnt(0)
	ds_write_b128 v140, v[110:113] offset:65024
	s_waitcnt lgkmcnt(0)
	s_barrier
	ds_read_b64_tr_b16 v[122:123], v121 offset:16384
	ds_read_b64_tr_b16 v[124:125], v121 offset:17408
	ds_read_b128 v[126:129], v0 offset:51200
	ds_read_b128 v[130:133], v0 offset:55808
	ds_read_b64_tr_b16 v[134:135], v119 offset:16384
	ds_read_b64_tr_b16 v[136:137], v119 offset:17408
	s_waitcnt lgkmcnt(2)
	v_mfma_f32_32x32x16_bf16 v[18:33], v[122:125], v[130:133], v[18:33]
	v_mfma_f32_32x32x16_bf16 v[50:65], v[122:125], v[126:129], v[50:65]
	s_waitcnt lgkmcnt(0)
	v_mfma_f32_32x32x16_bf16 v[34:49], v[134:137], v[126:129], v[34:49]
	ds_read_b64_tr_b16 v[122:123], v121 offset:20480
	ds_read_b64_tr_b16 v[124:125], v121 offset:21504
	ds_read_b128 v[126:129], v0 offset:51232
	v_mfma_f32_32x32x16_bf16 v[2:17], v[134:137], v[130:133], v[2:17]
	ds_read_b128 v[130:133], v0 offset:55840
	ds_read_b64_tr_b16 v[134:135], v119 offset:20480
	ds_read_b64_tr_b16 v[136:137], v119 offset:21504
	s_waitcnt lgkmcnt(3)
	v_mfma_f32_32x32x16_bf16 v[50:65], v[122:125], v[126:129], v[50:65]
	s_waitcnt lgkmcnt(2)
	v_mfma_f32_32x32x16_bf16 v[18:33], v[122:125], v[130:133], v[18:33]
	s_waitcnt lgkmcnt(0)
	v_mfma_f32_32x32x16_bf16 v[34:49], v[134:137], v[126:129], v[34:49]
	ds_read_b64_tr_b16 v[122:123], v121 offset:24576
	ds_read_b64_tr_b16 v[124:125], v121 offset:25600
	ds_read_b128 v[126:129], v0 offset:51264
	v_mfma_f32_32x32x16_bf16 v[2:17], v[134:137], v[130:133], v[2:17]
	ds_read_b128 v[130:133], v0 offset:55872
	ds_read_b64_tr_b16 v[134:135], v119 offset:24576
	ds_read_b64_tr_b16 v[136:137], v119 offset:25600
	s_waitcnt lgkmcnt(3)
	v_mfma_f32_32x32x16_bf16 v[50:65], v[122:125], v[126:129], v[50:65]
	s_waitcnt lgkmcnt(2)
	v_mfma_f32_32x32x16_bf16 v[18:33], v[122:125], v[130:133], v[18:33]
	s_waitcnt lgkmcnt(0)
	v_mfma_f32_32x32x16_bf16 v[34:49], v[134:137], v[126:129], v[34:49]
	ds_read_b64_tr_b16 v[122:123], v121 offset:28672
	ds_read_b64_tr_b16 v[124:125], v121 offset:29696
	ds_read_b128 v[126:129], v0 offset:51296
	v_mfma_f32_32x32x16_bf16 v[2:17], v[134:137], v[130:133], v[2:17]
	ds_read_b128 v[130:133], v0 offset:55904
	ds_read_b64_tr_b16 v[134:135], v119 offset:28672
	ds_read_b64_tr_b16 v[136:137], v119 offset:29696
	s_waitcnt lgkmcnt(3)
	v_mfma_f32_32x32x16_bf16 v[50:65], v[122:125], v[126:129], v[50:65]
	s_waitcnt lgkmcnt(2)
	v_mfma_f32_32x32x16_bf16 v[18:33], v[122:125], v[130:133], v[18:33]
	s_waitcnt lgkmcnt(0)
	v_mfma_f32_32x32x16_bf16 v[34:49], v[134:137], v[126:129], v[34:49]
	v_mfma_f32_32x32x16_bf16 v[2:17], v[134:137], v[130:133], v[2:17]
	s_lshl_b32 s0, s14, 1
	s_add_u32 s14, s22, s0
	s_addc_u32 s15, s23, 0
	s_ashr_i32 s0, s13, 1
	s_andn2_b32 s0, s0, 63
	s_ashr_i32 s1, s0, 31
	s_lshl_b64 s[0:1], s[0:1], 1
	s_add_u32 s0, s14, s0
	v_lshrrev_b32_e32 v0, 2, v115
	s_addc_u32 s1, s15, s1
	v_and_b32_e32 v0, 8, v0
	v_lshl_add_u64 v[66:67], s[0:1], 0, v[0:1]
	v_cmp_lt_i32_e32 vcc, -1, v120
	s_waitcnt lgkmcnt(0)
	s_barrier
	s_and_saveexec_b64 s[0:1], vcc
	s_cbranch_execz .LBB0_902
	v_mov_b32_e32 v121, v1
	v_lshlrev_b64 v[68:69], 11, v[120:121]
	v_pk_mul_f32 v[50:51], v[116:117], v[50:51] op_sel_hi:[0,1]
	v_pk_mul_f32 v[52:53], v[116:117], v[52:53] op_sel_hi:[0,1]
	v_pk_mul_f32 v[54:55], v[116:117], v[54:55] op_sel_hi:[0,1]
	v_pk_mul_f32 v[56:57], v[116:117], v[56:57] op_sel_hi:[0,1]
	v_pk_mul_f32 v[58:59], v[116:117], v[58:59] op_sel_hi:[0,1]
	v_pk_mul_f32 v[60:61], v[116:117], v[60:61] op_sel_hi:[0,1]
	v_pk_mul_f32 v[62:63], v[116:117], v[62:63] op_sel_hi:[0,1]
	v_pk_mul_f32 v[64:65], v[116:117], v[64:65] op_sel_hi:[0,1]
	v_pk_mul_f32 v[34:35], v[116:117], v[34:35] op_sel_hi:[0,1]
	v_pk_mul_f32 v[36:37], v[116:117], v[36:37] op_sel_hi:[0,1]
	v_pk_mul_f32 v[38:39], v[116:117], v[38:39] op_sel_hi:[0,1]
	v_pk_mul_f32 v[40:41], v[116:117], v[40:41] op_sel_hi:[0,1]
	v_pk_mul_f32 v[42:43], v[116:117], v[42:43] op_sel_hi:[0,1]
	v_pk_mul_f32 v[44:45], v[116:117], v[44:45] op_sel_hi:[0,1]
	v_pk_mul_f32 v[46:47], v[116:117], v[46:47] op_sel_hi:[0,1]
	v_pk_mul_f32 v[48:49], v[116:117], v[48:49] op_sel_hi:[0,1]
	v_lshl_add_u64 v[68:69], v[66:67], 0, v[68:69]
	v_lshl_add_u64 v[68:69], v[0:1], 0, v[68:69]
	v_cvt_pk_bf16_f32 v210, v50, v51
	v_cvt_pk_bf16_f32 v211, v52, v53
	v_cvt_pk_bf16_f32 v212, v54, v55
	v_cvt_pk_bf16_f32 v213, v56, v57
	v_cvt_pk_bf16_f32 v214, v58, v59
	v_cvt_pk_bf16_f32 v215, v60, v61
	v_cvt_pk_bf16_f32 v216, v62, v63
	v_cvt_pk_bf16_f32 v217, v64, v65
	v_cvt_pk_bf16_f32 v218, v34, v35
	v_cvt_pk_bf16_f32 v219, v36, v37
	v_cvt_pk_bf16_f32 v220, v38, v39
	v_cvt_pk_bf16_f32 v221, v40, v41
	v_cvt_pk_bf16_f32 v222, v42, v43
	v_cvt_pk_bf16_f32 v223, v44, v45
	v_cvt_pk_bf16_f32 v224, v46, v47
	v_cvt_pk_bf16_f32 v225, v48, v49
	s_nop 1
	v_permlane32_swap_b32_e32 v210, v212
	v_permlane32_swap_b32_e32 v211, v213
	v_permlane32_swap_b32_e32 v214, v216
	v_permlane32_swap_b32_e32 v215, v217
	v_permlane32_swap_b32_e32 v218, v220
	v_permlane32_swap_b32_e32 v219, v221
	v_permlane32_swap_b32_e32 v222, v224
	v_permlane32_swap_b32_e32 v223, v225
	global_store_dwordx4 v[68:69], v[210:213], off
	global_store_dwordx4 v[68:69], v[214:217], off offset:32
	global_store_dwordx4 v[68:69], v[218:221], off offset:64
	global_store_dwordx4 v[68:69], v[222:225], off offset:96
